# v023 + branch-GEMM seam hook de-serialised: 12 gate loads issued up front (+4 after group 1) into fresh registers with counted vmcnt, instead of 8 load-pair/vmcnt(0) round trips
# speedup vs baseline: 1.0075x; 1.0068x over previous
;     DI void hook(f32x4 (&acc)[2][2][4][2], const Unit& u, int r, int wr, int wc, int fr_, int fq_) const {
;         int fr = fr_, fq = fq_; asm volatile("" : "+v"(fr), "+v"(fq));
;         const int row0 = u.pm * BM + wr * 64 + fr, col0 = u.pn * BM + wc * 32 + 8 * fq;
; #pragma unroll
;         for (int ai = 0; ai < 2; ++ai) {
; #pragma unroll
;             for (int m = 0; m < 4; ++m) {
;                 const unsigned char* gp = Z + ((size_t)u.pm * 24 + (r - 1) * 8 + u.pn) * 65536 + (((((wr * 4 + wc) * 2 + ai) * 4 + m) * 64 + fq * 16 + fr) << 4);
;                 const u32x4 gn = *(const u32x4*)gp, gd = *(const u32x4*)(gp + 8 * 65536);
; #pragma unroll
;                 for (int bj = 0; bj < 2; ++bj) {
;                     f32x4 n0, n1, d0, d1; unpackq8(bj ? (u32x2){gn.z, gn.w} : (u32x2){gn.x, gn.y}, n0, n1); unpackq8(bj ? (u32x2){gd.z, gd.w} : (u32x2){gd.x, gd.y}, d0, d1);
; #pragma unroll
;                     for (int j = 0; j < 4; ++j) { acc[ai][bj][m][0][j] *= n0[j] * __builtin_amdgcn_rcpf(d0[j]); acc[ai][bj][m][1][j] *= n1[j] * __builtin_amdgcn_rcpf(d1[j]); }
;                 }
;             }
;         }
;     }
.LBB0_904:
	s_andn2_b64 vcc, exec, s[4:5]
	s_cbranch_vccnz .LBB0_906
	v_mov_b32_e32 v2, v1
	v_mov_b32_e32 v4, v160
	s_add_u32 s4, s34, s22
	s_addc_u32 s5, s35, 0
	v_lshlrev_b32_e32 v2, 4, v2
	s_lshl_b64 s[4:5], s[4:5], 16
	v_lshl_add_u32 v2, v4, 8, v2
	s_add_u32 s4, s71, s4
	v_add_u32_e32 v4, s82, v2
	s_addc_u32 s5, s72, s5
	v_ashrrev_i32_e32 v5, 31, v4
	v_lshl_add_u64 v[138:139], s[4:5], 0, v[4:5]
	v_add_co_u32_e32 v4, vcc, s77, v138
	v_addc_co_u32_e32 v5, vcc, 0, v139, vcc
	global_load_dwordx4 v[178:181], v[138:139], off
	global_load_dwordx4 v[182:185], v[4:5], off
	global_load_dwordx4 v[186:189], v[138:139], off offset:1024
	global_load_dwordx4 v[190:193], v[4:5], off offset:1024
	global_load_dwordx4 v[204:207], v[138:139], off offset:2048
	global_load_dwordx4 v[208:211], v[4:5], off offset:2048
	global_load_dwordx4 v[212:215], v[138:139], off offset:3072
	global_load_dwordx4 v[230:233], v[4:5], off offset:3072
	v_add_u32_e32 v4, s83, v2
	v_ashrrev_i32_e32 v5, 31, v4
	v_lshl_add_u64 v[138:139], s[4:5], 0, v[4:5]
	v_add_co_u32_e32 v4, vcc, s77, v138
	v_addc_co_u32_e32 v5, vcc, 0, v139, vcc
	global_load_dwordx4 v[234:237], v[138:139], off
	global_load_dwordx4 v[238:241], v[4:5], off
	global_load_dwordx4 v[242:245], v[138:139], off offset:1024
	global_load_dwordx4 v[246:249], v[4:5], off offset:1024
	s_waitcnt vmcnt(10) lgkmcnt(0)
	v_cvt_f32_ubyte3_e32 v173, v178
	v_cvt_f32_ubyte2_e32 v172, v178
	v_cvt_f32_ubyte1_e32 v175, v178
	v_cvt_f32_ubyte2_e32 v165, v182
	v_cvt_f32_ubyte3_e32 v171, v182
	v_cvt_f32_ubyte0_e32 v140, v182
	v_cvt_f32_ubyte1_e32 v141, v182
	v_cvt_f32_ubyte0_e32 v158, v183
	v_cvt_f32_ubyte1_e32 v159, v183
	v_cvt_f32_ubyte2_e32 v170, v183
	v_cvt_f32_ubyte3_e32 v176, v183
	v_rcp_iflag_f32_e32 v166, v165
	v_rcp_iflag_f32_e32 v167, v171
	v_rcp_iflag_f32_e32 v140, v140
	v_rcp_iflag_f32_e32 v141, v141
	v_rcp_iflag_f32_e32 v158, v158
	v_rcp_iflag_f32_e32 v159, v159
	v_rcp_iflag_f32_e32 v170, v170
	v_cvt_f32_ubyte0_e32 v174, v178
	v_pk_mul_f32 v[166:167], v[166:167], v[172:173]
	v_rcp_iflag_f32_e32 v171, v176
	v_pk_mul_f32 v[140:141], v[140:141], v[174:175]
	v_pk_mul_f32 v[132:133], v[132:133], v[166:167]
	v_cvt_f32_ubyte1_e32 v167, v179
	v_cvt_f32_ubyte0_e32 v166, v179
	v_pk_mul_f32 v[130:131], v[130:131], v[140:141]
	v_cvt_f32_ubyte3_e32 v141, v179
	v_cvt_f32_ubyte2_e32 v140, v179
	v_pk_mul_f32 v[134:135], v[158:159], v[166:167]
	v_cvt_f32_ubyte2_e32 v158, v184
	v_pk_mul_f32 v[126:127], v[126:127], v[134:135]
	v_cvt_f32_ubyte0_e32 v134, v184
	v_cvt_f32_ubyte1_e32 v135, v184
	v_cvt_f32_ubyte3_e32 v159, v184
	v_pk_mul_f32 v[140:141], v[170:171], v[140:141]
	v_rcp_iflag_f32_e32 v134, v134
	v_rcp_iflag_f32_e32 v135, v135
	v_rcp_iflag_f32_e32 v158, v158
	v_rcp_iflag_f32_e32 v159, v159
	v_pk_mul_f32 v[128:129], v[128:129], v[140:141]
	v_cvt_f32_ubyte0_e32 v140, v185
	v_cvt_f32_ubyte1_e32 v141, v185
	v_cvt_f32_ubyte2_e32 v165, v185
	v_cvt_f32_ubyte3_e32 v167, v185
	v_rcp_iflag_f32_e32 v140, v140
	v_rcp_iflag_f32_e32 v141, v141
	v_rcp_iflag_f32_e32 v166, v165
	v_rcp_iflag_f32_e32 v167, v167
	v_cvt_f32_ubyte3_e32 v169, v180
	v_cvt_f32_ubyte2_e32 v168, v180
	v_cvt_f32_ubyte1_e32 v171, v180
	v_cvt_f32_ubyte0_e32 v170, v180
	v_pk_mul_f32 v[134:135], v[134:135], v[170:171]
	v_pk_mul_f32 v[158:159], v[158:159], v[168:169]
	v_pk_mul_f32 v[122:123], v[122:123], v[134:135]
	v_pk_mul_f32 v[124:125], v[124:125], v[158:159]
	v_cvt_f32_ubyte3_e32 v135, v181
	v_cvt_f32_ubyte2_e32 v134, v181
	v_cvt_f32_ubyte1_e32 v159, v181
	v_cvt_f32_ubyte0_e32 v158, v181
	v_pk_mul_f32 v[136:137], v[140:141], v[158:159]
	v_pk_mul_f32 v[134:135], v[166:167], v[134:135]
	v_pk_mul_f32 v[118:119], v[118:119], v[136:137]
	v_pk_mul_f32 v[120:121], v[120:121], v[134:135]
	s_waitcnt vmcnt(8)
	v_cvt_f32_ubyte3_e32 v173, v186
	v_cvt_f32_ubyte2_e32 v165, v190
	v_cvt_f32_ubyte3_e32 v171, v190
	v_cvt_f32_ubyte0_e32 v140, v190
	v_cvt_f32_ubyte1_e32 v141, v190
	v_cvt_f32_ubyte0_e32 v158, v191
	v_cvt_f32_ubyte1_e32 v159, v191
	v_cvt_f32_ubyte2_e32 v170, v191
	v_cvt_f32_ubyte3_e32 v176, v191
	v_rcp_iflag_f32_e32 v166, v165
	v_rcp_iflag_f32_e32 v167, v171
	v_rcp_iflag_f32_e32 v140, v140
	v_rcp_iflag_f32_e32 v141, v141
	v_rcp_iflag_f32_e32 v158, v158
	v_rcp_iflag_f32_e32 v159, v159
	v_cvt_f32_ubyte2_e32 v172, v186
	v_rcp_iflag_f32_e32 v170, v170
	v_cvt_f32_ubyte1_e32 v175, v186
	v_cvt_f32_ubyte0_e32 v174, v186
	v_pk_mul_f32 v[166:167], v[166:167], v[172:173]
	v_rcp_iflag_f32_e32 v171, v176
	v_pk_mul_f32 v[140:141], v[140:141], v[174:175]
	v_pk_mul_f32 v[116:117], v[116:117], v[166:167]
	v_cvt_f32_ubyte1_e32 v167, v187
	v_cvt_f32_ubyte0_e32 v166, v187
	v_pk_mul_f32 v[114:115], v[114:115], v[140:141]
	v_cvt_f32_ubyte3_e32 v141, v187
	v_cvt_f32_ubyte2_e32 v140, v187
	v_pk_mul_f32 v[134:135], v[158:159], v[166:167]
	v_cvt_f32_ubyte2_e32 v158, v192
	v_pk_mul_f32 v[110:111], v[110:111], v[134:135]
	v_cvt_f32_ubyte0_e32 v134, v192
	v_cvt_f32_ubyte1_e32 v135, v192
	v_cvt_f32_ubyte3_e32 v159, v192
	v_pk_mul_f32 v[140:141], v[170:171], v[140:141]
	v_rcp_iflag_f32_e32 v134, v134
	v_rcp_iflag_f32_e32 v135, v135
	v_rcp_iflag_f32_e32 v158, v158
	v_rcp_iflag_f32_e32 v159, v159
	v_pk_mul_f32 v[112:113], v[112:113], v[140:141]
	v_cvt_f32_ubyte0_e32 v140, v193
	v_cvt_f32_ubyte1_e32 v141, v193
	v_cvt_f32_ubyte2_e32 v165, v193
	v_cvt_f32_ubyte3_e32 v167, v193
	v_rcp_iflag_f32_e32 v140, v140
	v_rcp_iflag_f32_e32 v141, v141
	v_rcp_iflag_f32_e32 v166, v165
	v_rcp_iflag_f32_e32 v167, v167
	v_cvt_f32_ubyte3_e32 v169, v188
	v_cvt_f32_ubyte2_e32 v168, v188
	v_cvt_f32_ubyte1_e32 v171, v188
	v_cvt_f32_ubyte0_e32 v170, v188
	v_pk_mul_f32 v[134:135], v[134:135], v[170:171]
	v_pk_mul_f32 v[158:159], v[158:159], v[168:169]
	v_pk_mul_f32 v[106:107], v[106:107], v[134:135]
	v_pk_mul_f32 v[108:109], v[108:109], v[158:159]
	v_cvt_f32_ubyte3_e32 v135, v189
	v_cvt_f32_ubyte2_e32 v134, v189
	v_cvt_f32_ubyte1_e32 v159, v189
	v_cvt_f32_ubyte0_e32 v158, v189
	v_pk_mul_f32 v[136:137], v[140:141], v[158:159]
	v_pk_mul_f32 v[134:135], v[166:167], v[134:135]
	v_pk_mul_f32 v[102:103], v[102:103], v[136:137]
	v_pk_mul_f32 v[104:105], v[104:105], v[134:135]
	global_load_dwordx4 v[178:181], v[138:139], off offset:2048
	global_load_dwordx4 v[182:185], v[4:5], off offset:2048
	global_load_dwordx4 v[186:189], v[138:139], off offset:3072
	global_load_dwordx4 v[190:193], v[4:5], off offset:3072
	s_waitcnt vmcnt(10)
;     DI void hook(f32x4 (&acc)[2][2][4][2], const Unit& u, int r, int wr, int wc, int fr_, int fq_) const {
;         int fr = fr_, fq = fq_; asm volatile("" : "+v"(fr), "+v"(fq));
;         const int row0 = u.pm * BM + wr * 64 + fr, col0 = u.pn * BM + wc * 32 + 8 * fq;
; #pragma unroll
;         for (int ai = 0; ai < 2; ++ai) {
; #pragma unroll
;             for (int m = 0; m < 4; ++m) {
;                 const unsigned char* gp = Z + ((size_t)u.pm * 24 + (r - 1) * 8 + u.pn) * 65536 + (((((wr * 4 + wc) * 2 + ai) * 4 + m) * 64 + fq * 16 + fr) << 4);
;                 const u32x4 gn = *(const u32x4*)gp, gd = *(const u32x4*)(gp + 8 * 65536);
; #pragma unroll
;                 for (int bj = 0; bj < 2; ++bj) {
;                     f32x4 n0, n1, d0, d1; unpackq8(bj ? (u32x2){gn.z, gn.w} : (u32x2){gn.x, gn.y}, n0, n1); unpackq8(bj ? (u32x2){gd.z, gd.w} : (u32x2){gd.x, gd.y}, d0, d1);
; #pragma unroll
;                     for (int j = 0; j < 4; ++j) { acc[ai][bj][m][0][j] *= n0[j] * __builtin_amdgcn_rcpf(d0[j]); acc[ai][bj][m][1][j] *= n1[j] * __builtin_amdgcn_rcpf(d1[j]); }
;                 }
;             }
;         }
;     }
	v_cvt_f32_ubyte3_e32 v173, v204
	v_cvt_f32_ubyte2_e32 v165, v208
	v_cvt_f32_ubyte3_e32 v171, v208
	v_cvt_f32_ubyte0_e32 v140, v208
	v_cvt_f32_ubyte1_e32 v141, v208
	v_cvt_f32_ubyte0_e32 v158, v209
	v_cvt_f32_ubyte1_e32 v159, v209
	v_cvt_f32_ubyte2_e32 v170, v209
	v_cvt_f32_ubyte3_e32 v176, v209
	v_rcp_iflag_f32_e32 v166, v165
	v_rcp_iflag_f32_e32 v167, v171
	v_rcp_iflag_f32_e32 v140, v140
	v_rcp_iflag_f32_e32 v141, v141
	v_rcp_iflag_f32_e32 v158, v158
	v_rcp_iflag_f32_e32 v159, v159
	v_cvt_f32_ubyte2_e32 v172, v204
	v_rcp_iflag_f32_e32 v170, v170
	v_cvt_f32_ubyte1_e32 v175, v204
	v_cvt_f32_ubyte0_e32 v174, v204
	v_pk_mul_f32 v[166:167], v[166:167], v[172:173]
	v_rcp_iflag_f32_e32 v171, v176
	v_pk_mul_f32 v[140:141], v[140:141], v[174:175]
	v_pk_mul_f32 v[100:101], v[100:101], v[166:167]
	v_cvt_f32_ubyte1_e32 v167, v205
	v_cvt_f32_ubyte0_e32 v166, v205
	v_pk_mul_f32 v[98:99], v[98:99], v[140:141]
	v_cvt_f32_ubyte3_e32 v141, v205
	v_cvt_f32_ubyte2_e32 v140, v205
	v_pk_mul_f32 v[134:135], v[158:159], v[166:167]
	v_cvt_f32_ubyte2_e32 v158, v210
	v_pk_mul_f32 v[94:95], v[94:95], v[134:135]
	v_cvt_f32_ubyte0_e32 v134, v210
	v_cvt_f32_ubyte1_e32 v135, v210
	v_cvt_f32_ubyte3_e32 v159, v210
	v_pk_mul_f32 v[140:141], v[170:171], v[140:141]
	v_rcp_iflag_f32_e32 v134, v134
	v_rcp_iflag_f32_e32 v135, v135
	v_rcp_iflag_f32_e32 v158, v158
	v_rcp_iflag_f32_e32 v159, v159
	v_pk_mul_f32 v[96:97], v[96:97], v[140:141]
	v_cvt_f32_ubyte0_e32 v140, v211
	v_cvt_f32_ubyte1_e32 v141, v211
	v_cvt_f32_ubyte2_e32 v165, v211
	v_cvt_f32_ubyte3_e32 v167, v211
	v_rcp_iflag_f32_e32 v140, v140
	v_rcp_iflag_f32_e32 v141, v141
	v_rcp_iflag_f32_e32 v166, v165
	v_rcp_iflag_f32_e32 v167, v167
	v_cvt_f32_ubyte3_e32 v169, v206
	v_cvt_f32_ubyte2_e32 v168, v206
	v_cvt_f32_ubyte1_e32 v171, v206
	v_cvt_f32_ubyte0_e32 v170, v206
	v_pk_mul_f32 v[134:135], v[134:135], v[170:171]
	v_pk_mul_f32 v[158:159], v[158:159], v[168:169]
	v_pk_mul_f32 v[90:91], v[90:91], v[134:135]
	v_pk_mul_f32 v[92:93], v[92:93], v[158:159]
	v_cvt_f32_ubyte3_e32 v135, v207
	v_cvt_f32_ubyte2_e32 v134, v207
	v_cvt_f32_ubyte1_e32 v159, v207
	v_cvt_f32_ubyte0_e32 v158, v207
	v_pk_mul_f32 v[136:137], v[140:141], v[158:159]
	v_pk_mul_f32 v[134:135], v[166:167], v[134:135]
	v_pk_mul_f32 v[86:87], v[86:87], v[136:137]
	v_pk_mul_f32 v[88:89], v[88:89], v[134:135]
	s_waitcnt vmcnt(8)
	v_cvt_f32_ubyte1_e32 v171, v212
	v_cvt_f32_ubyte0_e32 v4, v230
	v_cvt_f32_ubyte1_e32 v5, v230
	v_rcp_iflag_f32_e32 v4, v4
	v_rcp_iflag_f32_e32 v5, v5
	v_cvt_f32_ubyte2_e32 v158, v230
	v_cvt_f32_ubyte3_e32 v159, v230
	v_cvt_f32_ubyte2_e32 v166, v231
	v_cvt_f32_ubyte3_e32 v167, v231
	v_rcp_iflag_f32_e32 v158, v158
	v_rcp_iflag_f32_e32 v166, v166
	v_rcp_iflag_f32_e32 v159, v159
	v_rcp_iflag_f32_e32 v167, v167
	v_cvt_f32_ubyte0_e32 v138, v231
	v_cvt_f32_ubyte1_e32 v165, v231
	v_cvt_f32_ubyte0_e32 v170, v212
	v_rcp_iflag_f32_e32 v138, v138
	v_rcp_iflag_f32_e32 v139, v165
	v_pk_mul_f32 v[4:5], v[4:5], v[170:171]
	v_cvt_f32_ubyte3_e32 v169, v212
	v_cvt_f32_ubyte2_e32 v168, v212
	v_pk_mul_f32 v[82:83], v[82:83], v[4:5]
	v_cvt_f32_ubyte3_e32 v5, v213
	v_cvt_f32_ubyte2_e32 v4, v213
	v_pk_mul_f32 v[158:159], v[158:159], v[168:169]
	v_pk_mul_f32 v[4:5], v[166:167], v[4:5]
	v_pk_mul_f32 v[84:85], v[84:85], v[158:159]
	v_cvt_f32_ubyte1_e32 v159, v213
	v_cvt_f32_ubyte0_e32 v158, v213
	v_pk_mul_f32 v[80:81], v[80:81], v[4:5]
	v_cvt_f32_ubyte0_e32 v4, v232
	v_cvt_f32_ubyte1_e32 v5, v232
	v_pk_mul_f32 v[134:135], v[138:139], v[158:159]
	v_rcp_iflag_f32_e32 v4, v4
	v_rcp_iflag_f32_e32 v5, v5
	v_pk_mul_f32 v[78:79], v[78:79], v[134:135]
	v_cvt_f32_ubyte2_e32 v138, v232
	v_cvt_f32_ubyte3_e32 v139, v232
	v_cvt_f32_ubyte0_e32 v134, v233
	v_cvt_f32_ubyte1_e32 v135, v233
	v_cvt_f32_ubyte2_e32 v140, v233
	v_cvt_f32_ubyte3_e32 v141, v233
	v_rcp_iflag_f32_e32 v140, v140
	v_rcp_iflag_f32_e32 v141, v141
	v_rcp_iflag_f32_e32 v138, v138
	v_rcp_iflag_f32_e32 v139, v139
	v_cvt_f32_ubyte1_e32 v167, v214
	v_cvt_f32_ubyte0_e32 v166, v214
	v_pk_mul_f32 v[4:5], v[4:5], v[166:167]
	v_rcp_iflag_f32_e32 v134, v134
	v_rcp_iflag_f32_e32 v135, v135
	v_pk_mul_f32 v[74:75], v[74:75], v[4:5]
	v_cvt_f32_ubyte3_e32 v5, v215
	v_cvt_f32_ubyte2_e32 v4, v215
	v_cvt_f32_ubyte3_e32 v159, v214
	v_cvt_f32_ubyte2_e32 v158, v214
	v_pk_mul_f32 v[4:5], v[140:141], v[4:5]
	v_pk_mul_f32 v[138:139], v[138:139], v[158:159]
	v_pk_mul_f32 v[72:73], v[72:73], v[4:5]
	v_add_u32_e32 v4, s83, v2
	v_pk_mul_f32 v[76:77], v[76:77], v[138:139]
	v_cvt_f32_ubyte1_e32 v139, v215
	v_cvt_f32_ubyte0_e32 v138, v215
	v_ashrrev_i32_e32 v5, 31, v4
	v_pk_mul_f32 v[134:135], v[134:135], v[138:139]
	v_lshl_add_u64 v[138:139], s[4:5], 0, v[4:5]
	v_add_co_u32_e32 v4, vcc, s77, v138
	v_pk_mul_f32 v[70:71], v[70:71], v[134:135]
	s_nop 0
	v_addc_co_u32_e32 v5, vcc, 0, v139, vcc
	s_waitcnt vmcnt(6)
;     DI void hook(f32x4 (&acc)[2][2][4][2], const Unit& u, int r, int wr, int wc, int fr_, int fq_) const {
;         int fr = fr_, fq = fq_; asm volatile("" : "+v"(fr), "+v"(fq));
;         const int row0 = u.pm * BM + wr * 64 + fr, col0 = u.pn * BM + wc * 32 + 8 * fq;
; #pragma unroll
;         for (int ai = 0; ai < 2; ++ai) {
; #pragma unroll
;             for (int m = 0; m < 4; ++m) {
;                 const unsigned char* gp = Z + ((size_t)u.pm * 24 + (r - 1) * 8 + u.pn) * 65536 + (((((wr * 4 + wc) * 2 + ai) * 4 + m) * 64 + fq * 16 + fr) << 4);
;                 const u32x4 gn = *(const u32x4*)gp, gd = *(const u32x4*)(gp + 8 * 65536);
; #pragma unroll
;                 for (int bj = 0; bj < 2; ++bj) {
;                     f32x4 n0, n1, d0, d1; unpackq8(bj ? (u32x2){gn.z, gn.w} : (u32x2){gn.x, gn.y}, n0, n1); unpackq8(bj ? (u32x2){gd.z, gd.w} : (u32x2){gd.x, gd.y}, d0, d1);
; #pragma unroll
;                     for (int j = 0; j < 4; ++j) { acc[ai][bj][m][0][j] *= n0[j] * __builtin_amdgcn_rcpf(d0[j]); acc[ai][bj][m][1][j] *= n1[j] * __builtin_amdgcn_rcpf(d1[j]); }
;                 }
;             }
;         }
;     }
	v_cvt_f32_ubyte3_e32 v173, v234
	v_cvt_f32_ubyte2_e32 v165, v238
	v_cvt_f32_ubyte3_e32 v171, v238
	v_cvt_f32_ubyte0_e32 v2, v238
	v_cvt_f32_ubyte1_e32 v141, v238
	v_cvt_f32_ubyte0_e32 v158, v239
	v_cvt_f32_ubyte1_e32 v159, v239
	v_cvt_f32_ubyte2_e32 v170, v239
	v_cvt_f32_ubyte3_e32 v176, v239
	v_rcp_iflag_f32_e32 v166, v165
	v_rcp_iflag_f32_e32 v167, v171
	v_rcp_iflag_f32_e32 v140, v2
	v_rcp_iflag_f32_e32 v141, v141
	v_rcp_iflag_f32_e32 v158, v158
	v_rcp_iflag_f32_e32 v159, v159
	v_cvt_f32_ubyte2_e32 v172, v234
	v_rcp_iflag_f32_e32 v170, v170
	v_cvt_f32_ubyte1_e32 v175, v234
	v_cvt_f32_ubyte0_e32 v174, v234
	v_pk_mul_f32 v[166:167], v[166:167], v[172:173]
	v_rcp_iflag_f32_e32 v171, v176
	v_pk_mul_f32 v[140:141], v[140:141], v[174:175]
	v_pk_mul_f32 v[68:69], v[68:69], v[166:167]
	v_cvt_f32_ubyte1_e32 v167, v235
	v_cvt_f32_ubyte0_e32 v166, v235
	v_pk_mul_f32 v[66:67], v[66:67], v[140:141]
	v_cvt_f32_ubyte3_e32 v141, v235
	v_cvt_f32_ubyte2_e32 v140, v235
	v_pk_mul_f32 v[134:135], v[158:159], v[166:167]
	v_cvt_f32_ubyte0_e32 v2, v240
	v_pk_mul_f32 v[62:63], v[62:63], v[134:135]
	v_cvt_f32_ubyte1_e32 v135, v240
	v_cvt_f32_ubyte2_e32 v158, v240
	v_cvt_f32_ubyte3_e32 v159, v240
	v_pk_mul_f32 v[140:141], v[170:171], v[140:141]
	v_rcp_iflag_f32_e32 v134, v2
	v_rcp_iflag_f32_e32 v135, v135
	v_rcp_iflag_f32_e32 v158, v158
	v_rcp_iflag_f32_e32 v159, v159
	v_pk_mul_f32 v[64:65], v[64:65], v[140:141]
	v_cvt_f32_ubyte0_e32 v140, v241
	v_cvt_f32_ubyte1_e32 v141, v241
	v_cvt_f32_ubyte2_e32 v165, v241
	v_cvt_f32_ubyte3_e32 v167, v241
	v_rcp_iflag_f32_e32 v140, v140
	v_rcp_iflag_f32_e32 v141, v141
	v_rcp_iflag_f32_e32 v166, v165
	v_rcp_iflag_f32_e32 v167, v167
	v_cvt_f32_ubyte3_e32 v169, v236
	v_cvt_f32_ubyte2_e32 v168, v236
	v_cvt_f32_ubyte1_e32 v171, v236
	v_cvt_f32_ubyte0_e32 v170, v236
	v_pk_mul_f32 v[134:135], v[134:135], v[170:171]
	v_pk_mul_f32 v[158:159], v[158:159], v[168:169]
	v_pk_mul_f32 v[58:59], v[58:59], v[134:135]
	v_pk_mul_f32 v[60:61], v[60:61], v[158:159]
	v_cvt_f32_ubyte3_e32 v135, v237
	v_cvt_f32_ubyte2_e32 v134, v237
	v_cvt_f32_ubyte1_e32 v159, v237
	v_cvt_f32_ubyte0_e32 v158, v237
	v_pk_mul_f32 v[136:137], v[140:141], v[158:159]
	v_pk_mul_f32 v[134:135], v[166:167], v[134:135]
	v_pk_mul_f32 v[54:55], v[54:55], v[136:137]
	v_pk_mul_f32 v[56:57], v[56:57], v[134:135]
	s_waitcnt vmcnt(4)
	v_cvt_f32_ubyte3_e32 v173, v242
	v_cvt_f32_ubyte2_e32 v165, v246
	v_cvt_f32_ubyte3_e32 v171, v246
	v_cvt_f32_ubyte0_e32 v2, v246
	v_cvt_f32_ubyte1_e32 v141, v246
	v_cvt_f32_ubyte0_e32 v158, v247
	v_cvt_f32_ubyte1_e32 v159, v247
	v_cvt_f32_ubyte2_e32 v170, v247
	v_cvt_f32_ubyte3_e32 v176, v247
	v_rcp_iflag_f32_e32 v166, v165
	v_rcp_iflag_f32_e32 v167, v171
	v_rcp_iflag_f32_e32 v140, v2
	v_rcp_iflag_f32_e32 v141, v141
	v_rcp_iflag_f32_e32 v158, v158
	v_rcp_iflag_f32_e32 v159, v159
	v_cvt_f32_ubyte2_e32 v172, v242
	v_rcp_iflag_f32_e32 v170, v170
	v_cvt_f32_ubyte1_e32 v175, v242
	v_cvt_f32_ubyte0_e32 v174, v242
	v_pk_mul_f32 v[166:167], v[166:167], v[172:173]
	v_rcp_iflag_f32_e32 v171, v176
	v_pk_mul_f32 v[140:141], v[140:141], v[174:175]
	v_pk_mul_f32 v[52:53], v[52:53], v[166:167]
	v_cvt_f32_ubyte1_e32 v167, v243
	v_cvt_f32_ubyte0_e32 v166, v243
	v_pk_mul_f32 v[50:51], v[50:51], v[140:141]
	v_cvt_f32_ubyte3_e32 v141, v243
	v_cvt_f32_ubyte2_e32 v140, v243
	v_pk_mul_f32 v[134:135], v[158:159], v[166:167]
	v_cvt_f32_ubyte0_e32 v2, v248
	v_pk_mul_f32 v[46:47], v[46:47], v[134:135]
	v_cvt_f32_ubyte1_e32 v135, v248
	v_cvt_f32_ubyte2_e32 v158, v248
	v_cvt_f32_ubyte3_e32 v159, v248
	v_pk_mul_f32 v[140:141], v[170:171], v[140:141]
	v_rcp_iflag_f32_e32 v134, v2
	v_rcp_iflag_f32_e32 v135, v135
	v_rcp_iflag_f32_e32 v158, v158
	v_rcp_iflag_f32_e32 v159, v159
	v_pk_mul_f32 v[48:49], v[48:49], v[140:141]
	v_cvt_f32_ubyte0_e32 v140, v249
	v_cvt_f32_ubyte1_e32 v141, v249
	v_cvt_f32_ubyte2_e32 v165, v249
	v_cvt_f32_ubyte3_e32 v167, v249
	v_rcp_iflag_f32_e32 v140, v140
	v_rcp_iflag_f32_e32 v141, v141
	v_rcp_iflag_f32_e32 v166, v165
	v_rcp_iflag_f32_e32 v167, v167
	v_cvt_f32_ubyte3_e32 v169, v244
	v_cvt_f32_ubyte2_e32 v168, v244
	v_cvt_f32_ubyte1_e32 v171, v244
	v_cvt_f32_ubyte0_e32 v170, v244
	v_pk_mul_f32 v[134:135], v[134:135], v[170:171]
	v_pk_mul_f32 v[158:159], v[158:159], v[168:169]
	v_pk_mul_f32 v[42:43], v[42:43], v[134:135]
	v_pk_mul_f32 v[44:45], v[44:45], v[158:159]
	v_cvt_f32_ubyte3_e32 v135, v245
	v_cvt_f32_ubyte2_e32 v134, v245
	v_cvt_f32_ubyte1_e32 v159, v245
	v_cvt_f32_ubyte0_e32 v158, v245
	v_pk_mul_f32 v[136:137], v[140:141], v[158:159]
	v_pk_mul_f32 v[134:135], v[166:167], v[134:135]
	v_pk_mul_f32 v[38:39], v[38:39], v[136:137]
	v_pk_mul_f32 v[40:41], v[40:41], v[134:135]
	s_waitcnt vmcnt(2)
;     DI void hook(f32x4 (&acc)[2][2][4][2], const Unit& u, int r, int wr, int wc, int fr_, int fq_) const {
;         int fr = fr_, fq = fq_; asm volatile("" : "+v"(fr), "+v"(fq));
;         const int row0 = u.pm * BM + wr * 64 + fr, col0 = u.pn * BM + wc * 32 + 8 * fq;
; #pragma unroll
;         for (int ai = 0; ai < 2; ++ai) {
; #pragma unroll
;             for (int m = 0; m < 4; ++m) {
;                 const unsigned char* gp = Z + ((size_t)u.pm * 24 + (r - 1) * 8 + u.pn) * 65536 + (((((wr * 4 + wc) * 2 + ai) * 4 + m) * 64 + fq * 16 + fr) << 4);
;                 const u32x4 gn = *(const u32x4*)gp, gd = *(const u32x4*)(gp + 8 * 65536);
; #pragma unroll
;                 for (int bj = 0; bj < 2; ++bj) {
;                     f32x4 n0, n1, d0, d1; unpackq8(bj ? (u32x2){gn.z, gn.w} : (u32x2){gn.x, gn.y}, n0, n1); unpackq8(bj ? (u32x2){gd.z, gd.w} : (u32x2){gd.x, gd.y}, d0, d1);
; #pragma unroll
;                     for (int j = 0; j < 4; ++j) { acc[ai][bj][m][0][j] *= n0[j] * __builtin_amdgcn_rcpf(d0[j]); acc[ai][bj][m][1][j] *= n1[j] * __builtin_amdgcn_rcpf(d1[j]); }
;                 }
;             }
;         }
;     }
	v_cvt_f32_ubyte3_e32 v173, v178
	v_cvt_f32_ubyte2_e32 v165, v182
	v_cvt_f32_ubyte3_e32 v171, v182
	v_cvt_f32_ubyte0_e32 v2, v182
	v_cvt_f32_ubyte1_e32 v141, v182
	v_cvt_f32_ubyte0_e32 v158, v183
	v_cvt_f32_ubyte1_e32 v159, v183
	v_cvt_f32_ubyte2_e32 v170, v183
	v_cvt_f32_ubyte3_e32 v176, v183
	v_rcp_iflag_f32_e32 v166, v165
	v_rcp_iflag_f32_e32 v167, v171
	v_rcp_iflag_f32_e32 v140, v2
	v_rcp_iflag_f32_e32 v141, v141
	v_rcp_iflag_f32_e32 v158, v158
	v_rcp_iflag_f32_e32 v159, v159
	v_cvt_f32_ubyte2_e32 v172, v178
	v_rcp_iflag_f32_e32 v170, v170
	v_cvt_f32_ubyte1_e32 v175, v178
	v_cvt_f32_ubyte0_e32 v174, v178
	v_pk_mul_f32 v[166:167], v[166:167], v[172:173]
	v_rcp_iflag_f32_e32 v171, v176
	v_pk_mul_f32 v[140:141], v[140:141], v[174:175]
	v_pk_mul_f32 v[36:37], v[36:37], v[166:167]
	v_cvt_f32_ubyte1_e32 v167, v179
	v_cvt_f32_ubyte0_e32 v166, v179
	v_pk_mul_f32 v[34:35], v[34:35], v[140:141]
	v_cvt_f32_ubyte3_e32 v141, v179
	v_cvt_f32_ubyte2_e32 v140, v179
	v_pk_mul_f32 v[134:135], v[158:159], v[166:167]
	v_cvt_f32_ubyte0_e32 v2, v184
	v_pk_mul_f32 v[30:31], v[30:31], v[134:135]
	v_cvt_f32_ubyte1_e32 v135, v184
	v_cvt_f32_ubyte2_e32 v158, v184
	v_cvt_f32_ubyte3_e32 v159, v184
	v_pk_mul_f32 v[140:141], v[170:171], v[140:141]
	v_rcp_iflag_f32_e32 v134, v2
	v_rcp_iflag_f32_e32 v135, v135
	v_rcp_iflag_f32_e32 v158, v158
	v_rcp_iflag_f32_e32 v159, v159
	v_pk_mul_f32 v[32:33], v[32:33], v[140:141]
	v_cvt_f32_ubyte0_e32 v140, v185
	v_cvt_f32_ubyte1_e32 v141, v185
	v_cvt_f32_ubyte2_e32 v165, v185
	v_cvt_f32_ubyte3_e32 v167, v185
	v_rcp_iflag_f32_e32 v140, v140
	v_rcp_iflag_f32_e32 v141, v141
	v_rcp_iflag_f32_e32 v166, v165
	v_rcp_iflag_f32_e32 v167, v167
	v_cvt_f32_ubyte3_e32 v169, v180
	v_cvt_f32_ubyte2_e32 v168, v180
	v_cvt_f32_ubyte1_e32 v171, v180
	v_cvt_f32_ubyte0_e32 v170, v180
	v_pk_mul_f32 v[134:135], v[134:135], v[170:171]
	v_pk_mul_f32 v[158:159], v[158:159], v[168:169]
	v_pk_mul_f32 v[26:27], v[26:27], v[134:135]
	v_pk_mul_f32 v[28:29], v[28:29], v[158:159]
	v_cvt_f32_ubyte3_e32 v135, v181
	v_cvt_f32_ubyte2_e32 v134, v181
	v_cvt_f32_ubyte1_e32 v159, v181
	v_cvt_f32_ubyte0_e32 v158, v181
	v_pk_mul_f32 v[136:137], v[140:141], v[158:159]
	v_pk_mul_f32 v[134:135], v[166:167], v[134:135]
	v_pk_mul_f32 v[22:23], v[22:23], v[136:137]
	v_pk_mul_f32 v[24:25], v[24:25], v[134:135]
	s_waitcnt vmcnt(0)
	v_cvt_f32_ubyte1_e32 v171, v186
	v_cvt_f32_ubyte0_e32 v2, v190
	v_cvt_f32_ubyte1_e32 v5, v190
	v_cvt_f32_ubyte2_e32 v158, v190
	v_cvt_f32_ubyte3_e32 v159, v190
	v_rcp_iflag_f32_e32 v4, v2
	v_rcp_iflag_f32_e32 v5, v5
	v_cvt_f32_ubyte2_e32 v166, v191
	v_cvt_f32_ubyte3_e32 v167, v191
	v_rcp_iflag_f32_e32 v158, v158
	v_rcp_iflag_f32_e32 v159, v159
	v_cvt_f32_ubyte0_e32 v138, v191
	v_cvt_f32_ubyte1_e32 v165, v191
	v_rcp_iflag_f32_e32 v166, v166
	v_rcp_iflag_f32_e32 v167, v167
	v_rcp_iflag_f32_e32 v138, v138
	v_rcp_iflag_f32_e32 v139, v165
	v_cvt_f32_ubyte0_e32 v170, v186
	v_cvt_f32_ubyte3_e32 v169, v186
	v_cvt_f32_ubyte2_e32 v168, v186
	v_pk_mul_f32 v[4:5], v[4:5], v[170:171]
	v_pk_mul_f32 v[158:159], v[158:159], v[168:169]
	v_pk_mul_f32 v[18:19], v[18:19], v[4:5]
	v_cvt_f32_ubyte3_e32 v5, v187
	v_cvt_f32_ubyte2_e32 v4, v187
	v_pk_mul_f32 v[20:21], v[20:21], v[158:159]
	v_cvt_f32_ubyte1_e32 v159, v187
	v_cvt_f32_ubyte0_e32 v158, v187
	v_pk_mul_f32 v[4:5], v[166:167], v[4:5]
	v_pk_mul_f32 v[134:135], v[138:139], v[158:159]
	v_pk_mul_f32 v[16:17], v[16:17], v[4:5]
	v_cvt_f32_ubyte0_e32 v2, v192
	v_cvt_f32_ubyte1_e32 v5, v192
	v_cvt_f32_ubyte2_e32 v138, v192
	v_cvt_f32_ubyte3_e32 v139, v192
	v_rcp_iflag_f32_e32 v4, v2
	v_rcp_iflag_f32_e32 v5, v5
	v_rcp_iflag_f32_e32 v138, v138
	v_rcp_iflag_f32_e32 v139, v139
	v_pk_mul_f32 v[14:15], v[14:15], v[134:135]
	v_cvt_f32_ubyte0_e32 v134, v193
	v_cvt_f32_ubyte1_e32 v135, v193
	v_cvt_f32_ubyte2_e32 v140, v193
	v_cvt_f32_ubyte3_e32 v141, v193
	v_rcp_iflag_f32_e32 v134, v134
	v_rcp_iflag_f32_e32 v135, v135
	v_rcp_iflag_f32_e32 v140, v140
	v_rcp_iflag_f32_e32 v141, v141
	v_cvt_f32_ubyte3_e32 v159, v188
	v_cvt_f32_ubyte2_e32 v158, v188
	v_cvt_f32_ubyte1_e32 v167, v188
	v_cvt_f32_ubyte0_e32 v166, v188
	v_pk_mul_f32 v[4:5], v[4:5], v[166:167]
	v_pk_mul_f32 v[138:139], v[138:139], v[158:159]
	v_pk_mul_f32 v[10:11], v[10:11], v[4:5]
	v_pk_mul_f32 v[12:13], v[12:13], v[138:139]
	v_cvt_f32_ubyte3_e32 v5, v189
	v_cvt_f32_ubyte2_e32 v4, v189
	v_cvt_f32_ubyte1_e32 v139, v189
	v_cvt_f32_ubyte0_e32 v138, v189
	v_pk_mul_f32 v[134:135], v[134:135], v[138:139]
	v_pk_mul_f32 v[4:5], v[140:141], v[4:5]
	v_pk_mul_f32 v[6:7], v[6:7], v[134:135]
	v_pk_mul_f32 v[8:9], v[8:9], v[4:5]
